# v26 + NA loop: the 8 exec-masked single bias lookups per key row batched (unmasked reads of clamped indices, one wait, mask via v_cndmask with -inf)
# speedup vs baseline: 1.0080x; 1.0014x over previous
; #define LAS __attribute__((address_space(3)))
; __global__ void __launch_bounds__(NTHR, 2) fwd_megakernel(Params P) {
;     ...
;                 for (int kr = 0; kr < 2; ++kr) {
;                     const int kb = kr * 64 + cbase;
;                     const int dr = (r0 + 2 * c + kr) - rr + 7;
;                     const LAS float* lrow = lutl + head * 465 + dr * 31;
;                     LAS const unsigned char* kp = Kb + (kb + i) * 128;
;                     const bf16x8 a00 = *(LAS const bf16x8*)(kp + xk0), a10 = *(LAS const bf16x8*)(kp + 16 * 128 + xk0);
;                     const bf16x8 a01 = *(LAS const bf16x8*)(kp + xk1), a11 = *(LAS const bf16x8*)(kp + 16 * 128 + xk1);
;                     const float nm = -mr;
;                     f32x4 s0 = {nm, nm, nm, nm}, s1 = s0;
;                     s0 = __builtin_amdgcn_mfma_f32_16x16x32_bf16(a00, qf0, s0, 0, 0, 0); s1 = __builtin_amdgcn_mfma_f32_16x16x32_bf16(a10, qf0, s1, 0, 0, 0);
;                     s0 = __builtin_amdgcn_mfma_f32_16x16x32_bf16(a01, qf1, s0, 0, 0, 0); s1 = __builtin_amdgcn_mfma_f32_16x16x32_bf16(a11, qf1, s1, 0, 0, 0);
; #pragma unroll
;                     for (int j = 0; j < 4; ++j) {
;                         s0[j] = ((okm >> j) & 1u) ? s0[j] + lrow[bidx[j]] : -INFINITY;
;                         s1[j] = ((okm >> (4 + j)) & 1u) ? s1[j] + lrow[bidx[4 + j]] : -INFINITY;
;                     }
;                     float mx = fmaxf(fmaxf(fmaxf(s0[0], s0[1]), fmaxf(s0[2], s0[3])), fmaxf(fmaxf(s1[0], s1[1]), fmaxf(s1[2], s1[3])));
;                     if (__any(mx > THR)) {
;                         mx = fmaxf(mx, __shfl_xor(mx, 16)); mx = fmaxf(mx, __shfl_xor(mx, 32));
;                         const float dlt = fmaxf(mx, 0.f);
;                         const float alpha = __builtin_amdgcn_exp2f(-dlt);
;                         mr += dlt; lr *= alpha;
; #pragma unroll
;                         for (int db = 0; db < 4; ++db) o[db] = o[db] * alpha;
;                         s0 = s0 - dlt; s1 = s1 - dlt;
;                     }
.LBB0_713:
	s_add_i32 s13, s69, s59
	v_add_u32_e32 v34, s13, v70
	v_add_u32_e32 v35, v34, v60
	ds_read_b128 v[38:41], v35
	ds_read_b128 v[42:45], v35 offset:2048
	v_add_u32_e32 v46, v34, v69
	ds_read_b128 v[76:79], v46
	ds_read_b128 v[82:85], v46 offset:2048
	s_lshr_b32 s11, s97, 2
	v_xor_b32_e32 v34, 0x80000000, v74
	s_add_i32 s11, s11, s18
	v_mov_b32_e32 v35, v34
	v_mov_b32_e32 v36, v34
	v_mov_b32_e32 v37, v34
	s_bfe_u32 s9, s11, 0x60001
	s_lshl_b32 s1, s11, 1
	s_waitcnt lgkmcnt(0)
	v_mfma_f32_16x16x32_bf16 v[38:41], v[38:41], v[8:11], v[34:37]
	s_and_b32 s1, s1, 2
	v_sub_u32_e64 v12, s9, 4 clamp
	s_lshl_b32 s6, s54, 1
	v_mfma_f32_16x16x32_bf16 v[86:89], v[42:45], v[8:11], v[34:37]
	s_add_i32 s1, s1, s64
	v_min_u32_e32 v12, 56, v12
	s_sub_i32 s6, s6, s9
	v_add_u32_e32 v12, s6, v12
	s_mul_i32 s6, s1, 0x744
	s_movk_i32 s7, 0x7c
	s_add_i32 s6, s6, 0
	v_mfma_f32_16x16x32_bf16 v[44:47], v[76:79], v[14:17], v[38:41]
	v_mul_lo_u32 v12, v12, s7
	v_add_u32_e32 v12, s6, v12
	v_add_u32_e32 v81, 0x20000, v12
	v_mfma_f32_16x16x32_bf16 v[40:43], v[82:85], v[14:17], v[86:89]
	v_mov_b32_e32 v12, 0xff800000
	v_lshl_add_u32 v53, v61, 2, v81
	v_mov_b32_e32 v36, 0xff800000
	v_lshl_add_u32 v55, v65, 2, v81
	v_lshl_add_u32 v76, v62, 2, v81
	v_lshl_add_u32 v77, v66, 2, v81
	v_lshl_add_u32 v78, v63, 2, v81
	v_lshl_add_u32 v79, v67, 2, v81
	v_lshl_add_u32 v80, v64, 2, v81
	v_lshl_add_u32 v81, v68, 2, v81
	v_mov_b32_e32 v208, 0xff800000
	ds_read_b32 v200, v53 offset:868
	ds_read_b32 v201, v55 offset:868
	ds_read_b32 v202, v76 offset:868
	ds_read_b32 v203, v77 offset:868
	ds_read_b32 v204, v78 offset:868
	ds_read_b32 v205, v79 offset:868
	ds_read_b32 v206, v80 offset:868
	ds_read_b32 v207, v81 offset:868
	s_waitcnt lgkmcnt(0)
	v_add_f32_e32 v200, v44, v200
	v_add_f32_e32 v201, v40, v201
	v_add_f32_e32 v202, v45, v202
	v_add_f32_e32 v203, v41, v203
	v_add_f32_e32 v204, v46, v204
	v_add_f32_e32 v205, v42, v205
	v_add_f32_e32 v206, v47, v206
	v_add_f32_e32 v207, v43, v207
	v_cndmask_b32_e64 v36, v208, v200, s[4:5]
	v_cndmask_b32_e64 v12, v208, v201, s[90:91]
	v_cndmask_b32_e64 v37, v208, v202, s[30:31]
	v_cndmask_b32_e64 v35, v208, v203, s[92:93]
	v_cndmask_b32_e64 v40, v208, v204, s[82:83]
	v_cndmask_b32_e64 v38, v208, v205, s[94:95]
	v_cndmask_b32_e64 v41, v208, v206, s[88:89]
	v_cndmask_b32_e64 v39, v208, v207, s[2:3]
	v_max_f32_e32 v42, v37, v37
	v_max_f32_e32 v43, v36, v36
	v_max_f32_e32 v42, v43, v42
	v_max_f32_e32 v43, v41, v41
	v_max_f32_e32 v44, v40, v40
	v_max_f32_e32 v43, v44, v43
	v_max_f32_e32 v44, v39, v39
	v_max_f32_e32 v45, v38, v38
	v_max_f32_e32 v44, v45, v44
	v_max3_f32 v44, v12, v35, v44
	v_max3_f32 v42, v42, v43, v44
	v_cmp_lt_f32_e32 vcc, s66, v42
	s_cbranch_vccz .LBB0_731
	v_and_b32_e32 v43, 64, v238
	v_xor_b32_e32 v34, 16, v238
	v_add_u32_e32 v43, 64, v43
	v_cmp_lt_i32_e32 vcc, v34, v43
	s_nop 1
	v_cndmask_b32_e32 v34, v238, v34, vcc
	v_lshlrev_b32_e32 v34, 2, v34
	ds_bpermute_b32 v34, v34, v42
	v_max_f32_e32 v42, v42, v42
	s_waitcnt lgkmcnt(0)
	v_max_f32_e32 v34, v34, v34
	v_max_f32_e32 v34, v42, v34
	v_xor_b32_e32 v42, 32, v238
	v_cmp_lt_i32_e32 vcc, v42, v43
	s_nop 1
	v_cndmask_b32_e32 v42, v238, v42, vcc
	v_lshlrev_b32_e32 v42, 2, v42
	ds_bpermute_b32 v42, v42, v34
	s_waitcnt lgkmcnt(0)
	v_max3_f32 v42, v34, v42, 0
	v_exp_f32_e64 v34, -v42
	v_add_f32_e32 v74, v74, v42
	v_sub_f32_e32 v41, v41, v42
	v_sub_f32_e32 v40, v40, v42
	v_pk_mul_f32 v[32:33], v[34:35], v[32:33] op_sel_hi:[0,1]
	v_pk_mul_f32 v[30:31], v[34:35], v[30:31] op_sel_hi:[0,1]
	v_pk_mul_f32 v[28:29], v[34:35], v[28:29] op_sel_hi:[0,1]
	v_pk_mul_f32 v[26:27], v[34:35], v[26:27] op_sel_hi:[0,1]
	v_pk_mul_f32 v[24:25], v[34:35], v[24:25] op_sel_hi:[0,1]
	v_pk_mul_f32 v[22:23], v[34:35], v[22:23] op_sel_hi:[0,1]
	v_pk_mul_f32 v[20:21], v[34:35], v[20:21] op_sel_hi:[0,1]
	v_pk_mul_f32 v[18:19], v[34:35], v[18:19] op_sel_hi:[0,1]
	v_mul_f32_e32 v75, v75, v34
	v_sub_f32_e32 v37, v37, v42
	v_sub_f32_e32 v36, v36, v42
	v_sub_f32_e32 v39, v39, v42
	v_sub_f32_e32 v38, v38, v42
	v_sub_f32_e32 v35, v35, v42
	v_sub_f32_e32 v12, v12, v42
	v_xor_b32_e32 v34, 0x80000000, v74
; __global__ void __launch_bounds__(NTHR, 2) fwd_megakernel(Params P) {
;     ...
;                 for (int kr = 0; kr < 2; ++kr) {
;                     const int kb = kr * 64 + cbase;
;                     const int dr = (r0 + 2 * c + kr) - rr + 7;
;                     const LAS float* lrow = lutl + head * 465 + dr * 31;
;                     LAS const unsigned char* kp = Kb + (kb + i) * 128;
;                     const bf16x8 a00 = *(LAS const bf16x8*)(kp + xk0), a10 = *(LAS const bf16x8*)(kp + 16 * 128 + xk0);
;                     const bf16x8 a01 = *(LAS const bf16x8*)(kp + xk1), a11 = *(LAS const bf16x8*)(kp + 16 * 128 + xk1);
;                     const float nm = -mr;
;                     f32x4 s0 = {nm, nm, nm, nm}, s1 = s0;
;                     s0 = __builtin_amdgcn_mfma_f32_16x16x32_bf16(a00, qf0, s0, 0, 0, 0); s1 = __builtin_amdgcn_mfma_f32_16x16x32_bf16(a10, qf0, s1, 0, 0, 0);
;                     s0 = __builtin_amdgcn_mfma_f32_16x16x32_bf16(a01, qf1, s0, 0, 0, 0); s1 = __builtin_amdgcn_mfma_f32_16x16x32_bf16(a11, qf1, s1, 0, 0, 0);
; #pragma unroll
;                     for (int j = 0; j < 4; ++j) {
;                         s0[j] = ((okm >> j) & 1u) ? s0[j] + lrow[bidx[j]] : -INFINITY;
;                         s1[j] = ((okm >> (4 + j)) & 1u) ? s1[j] + lrow[bidx[4 + j]] : -INFINITY;
;                     }
;                     float mx = fmaxf(fmaxf(fmaxf(s0[0], s0[1]), fmaxf(s0[2], s0[3])), fmaxf(fmaxf(s1[0], s1[1]), fmaxf(s1[2], s1[3])));
;                     if (__any(mx > THR)) {
;                         mx = fmaxf(mx, __shfl_xor(mx, 16)); mx = fmaxf(mx, __shfl_xor(mx, 32));
;                         const float dlt = fmaxf(mx, 0.f);
;                         const float alpha = __builtin_amdgcn_exp2f(-dlt);
;                         mr += dlt; lr *= alpha;
; #pragma unroll
;                         for (int db = 0; db < 4; ++db) o[db] = o[db] * alpha;
;                         s0 = s0 - dlt; s1 = s1 - dlt;
;                     }
;                     float p0[4], p1[4]; float ps = 0.f;
; #pragma unroll
;                     for (int j = 0; j < 4; ++j) { p0[j] = __builtin_amdgcn_exp2f(s0[j]); p1[j] = __builtin_amdgcn_exp2f(s1[j]); ps += p0[j] + p1[j]; }
;                     lr += ps;
;                     u32x4 w; w.x = pk2(p0[0], p0[1]); w.y = pk2(p0[2], p0[3]); w.z = pk2(p1[0], p1[1]); w.w = pk2(p1[2], p1[3]);
.LBB0_731:
	v_exp_f32_e32 v83, v12
	v_add_u32_e32 v12, s13, v71
	v_exp_f32_e32 v85, v35
	v_add_u32_e32 v35, v12, v56
	v_exp_f32_e32 v82, v36
	v_exp_f32_e32 v84, v37
	v_exp_f32_e32 v86, v40
	v_exp_f32_e32 v87, v38
	v_exp_f32_e32 v88, v41
	s_waitcnt vmcnt(0)
	ds_read_b64_tr_b16 v[40:41], v35 offset:32768
	ds_read_b64_tr_b16 v[42:43], v35 offset:34816
	v_exp_f32_e32 v89, v39
	v_add_u32_e32 v35, v12, v57
	ds_read_b64_tr_b16 v[44:45], v35 offset:32768
	ds_read_b64_tr_b16 v[46:47], v35 offset:34816
	v_cvt_pk_bf16_f32 v36, v82, v84
	v_cvt_pk_bf16_f32 v37, v86, v88
	v_cvt_pk_bf16_f32 v38, v83, v85
	v_cvt_pk_bf16_f32 v39, v87, v89
	v_add_u32_e32 v35, v12, v58
	v_add_u32_e32 v12, v12, v59
	s_waitcnt lgkmcnt(2)
	v_mfma_f32_16x16x32_bf16 v[18:21], v[40:43], v[36:39], v[18:21]
	ds_read_b64_tr_b16 v[40:41], v35 offset:32768
	ds_read_b64_tr_b16 v[42:43], v35 offset:34816
	v_mov_b32_e32 v35, v34
	s_waitcnt lgkmcnt(2)
	v_mfma_f32_16x16x32_bf16 v[22:25], v[44:47], v[36:39], v[22:25]
	ds_read_b64_tr_b16 v[44:45], v12 offset:32768
	ds_read_b64_tr_b16 v[46:47], v12 offset:34816
	v_add_u32_e32 v12, s13, v72
	v_add_u32_e32 v90, v12, v60
	s_waitcnt lgkmcnt(2)
	v_mfma_f32_16x16x32_bf16 v[26:29], v[40:43], v[36:39], v[26:29]
	ds_read_b128 v[40:43], v90
	v_add_u32_e32 v12, v12, v69
	s_waitcnt lgkmcnt(1)
	v_mfma_f32_16x16x32_bf16 v[30:33], v[44:47], v[36:39], v[30:33]
	v_mov_b32_e32 v36, v34
	v_mov_b32_e32 v37, v34
	s_waitcnt lgkmcnt(0)
	s_nop 0
	v_mfma_f32_16x16x32_bf16 v[38:41], v[40:43], v[8:11], v[34:37]
	ds_read_b128 v[42:45], v90 offset:2048
	s_waitcnt lgkmcnt(0)
	v_mfma_f32_16x16x32_bf16 v[34:37], v[42:45], v[8:11], v[34:37]
	ds_read_b128 v[42:45], v12
	s_waitcnt lgkmcnt(0)
	v_mfma_f32_16x16x32_bf16 v[44:47], v[42:45], v[14:17], v[38:41]
	s_nop 2
	ds_read_b128 v[38:41], v12 offset:2048
	v_mov_b32_e32 v12, 0xff800000
	s_waitcnt lgkmcnt(0)
	v_mfma_f32_16x16x32_bf16 v[40:43], v[38:41], v[14:17], v[34:37]
	s_nop 2
	v_mov_b32_e32 v34, 0xff800000
	v_mov_b32_e32 v208, 0xff800000
	ds_read_b32 v200, v53 offset:992
	ds_read_b32 v201, v55 offset:992
	ds_read_b32 v202, v76 offset:992
	ds_read_b32 v203, v77 offset:992
	ds_read_b32 v204, v78 offset:992
	ds_read_b32 v205, v79 offset:992
	ds_read_b32 v206, v80 offset:992
	ds_read_b32 v207, v81 offset:992
	s_waitcnt lgkmcnt(0)
	v_add_f32_e32 v200, v44, v200
	v_add_f32_e32 v201, v40, v201
	v_add_f32_e32 v202, v45, v202
	v_add_f32_e32 v203, v41, v203
	v_add_f32_e32 v204, v46, v204
	v_add_f32_e32 v205, v42, v205
	v_add_f32_e32 v206, v47, v206
	v_add_f32_e32 v207, v43, v207
	v_cndmask_b32_e64 v34, v208, v200, s[4:5]
	v_cndmask_b32_e64 v12, v208, v201, s[90:91]
	v_cndmask_b32_e64 v37, v208, v202, s[30:31]
	v_cndmask_b32_e64 v35, v208, v203, s[92:93]
	v_cndmask_b32_e64 v38, v208, v204, s[82:83]
	v_cndmask_b32_e64 v36, v208, v205, s[94:95]
	v_cndmask_b32_e64 v41, v208, v206, s[88:89]
	v_cndmask_b32_e64 v39, v208, v207, s[2:3]
	v_add_f32_e32 v40, v82, v83
	v_add_f32_e32 v42, v84, v85
	v_add_f32_e32 v40, 0, v40
	v_add_f32_e32 v43, v86, v87
	v_add_f32_e32 v40, v40, v42
	v_add_f32_e32 v44, v88, v89
	v_add_f32_e32 v40, v40, v43
	v_max_f32_e32 v42, v37, v37
	v_max_f32_e32 v43, v34, v34
	v_add_f32_e32 v40, v40, v44
	v_max_f32_e32 v42, v43, v42
	v_max_f32_e32 v43, v41, v41
	v_max_f32_e32 v44, v38, v38
	v_max_f32_e32 v43, v44, v43
	v_max_f32_e32 v44, v39, v39
	v_max_f32_e32 v45, v36, v36
	v_max_f32_e32 v44, v45, v44
	v_max3_f32 v44, v12, v35, v44
	v_max3_f32 v42, v42, v43, v44
	v_add_f32_e32 v40, v75, v40
	v_cmp_lt_f32_e32 vcc, s66, v42
	s_cbranch_vccz .LBB0_749
	v_and_b32_e32 v44, 64, v238
	v_xor_b32_e32 v43, 16, v238
	v_add_u32_e32 v44, 64, v44
	v_cmp_lt_i32_e32 vcc, v43, v44
	s_nop 1
	v_cndmask_b32_e32 v43, v238, v43, vcc
	v_lshlrev_b32_e32 v43, 2, v43
	ds_bpermute_b32 v43, v43, v42
	v_max_f32_e32 v42, v42, v42
	s_waitcnt lgkmcnt(0)
	v_max_f32_e32 v43, v43, v43
	v_max_f32_e32 v42, v42, v43
	v_xor_b32_e32 v43, 32, v238
	v_cmp_lt_i32_e32 vcc, v43, v44
	s_nop 1
	v_cndmask_b32_e32 v43, v238, v43, vcc
	v_lshlrev_b32_e32 v43, 2, v43
	ds_bpermute_b32 v43, v43, v42
	s_waitcnt lgkmcnt(0)
	v_max3_f32 v43, v42, v43, 0
	v_exp_f32_e64 v42, -v43
	v_add_f32_e32 v74, v74, v43
	v_sub_f32_e32 v41, v41, v43
	v_sub_f32_e32 v38, v38, v43
	v_pk_mul_f32 v[20:21], v[42:43], v[20:21] op_sel_hi:[0,1]
	v_pk_mul_f32 v[18:19], v[42:43], v[18:19] op_sel_hi:[0,1]
	v_pk_mul_f32 v[24:25], v[42:43], v[24:25] op_sel_hi:[0,1]
	v_pk_mul_f32 v[22:23], v[42:43], v[22:23] op_sel_hi:[0,1]
	v_pk_mul_f32 v[28:29], v[42:43], v[28:29] op_sel_hi:[0,1]
	v_pk_mul_f32 v[26:27], v[42:43], v[26:27] op_sel_hi:[0,1]
	v_pk_mul_f32 v[32:33], v[42:43], v[32:33] op_sel_hi:[0,1]
	v_pk_mul_f32 v[30:31], v[42:43], v[30:31] op_sel_hi:[0,1]
	v_mul_f32_e32 v40, v40, v42
	v_sub_f32_e32 v37, v37, v43
	v_sub_f32_e32 v34, v34, v43
	v_sub_f32_e32 v39, v39, v43
	v_sub_f32_e32 v36, v36, v43
	v_sub_f32_e32 v35, v35, v43
	v_sub_f32_e32 v12, v12, v43
